# NSA selected+window loops: V tile staged row-major in LDS (one ds_write_b128) and consumed with ds_read_b64_tr_b16 transposed reads; removes the DPP/bit-shuffle transpose
# speedup vs baseline: 1.0469x; 1.0066x over previous
; #define LAS __attribute__((address_space(3)))
; DI void kv_store(const KVRegs& r, LAS bf16_t* Ks, LAS bf16_t* Vt, int vstride, int vcol0, int tid) {
;   asm volatile("" : "+v"(tid));
;   const int key = tid >> 3, d8 = (tid & 7) * 8;
;   *(LAS u32x4*)(Ks + key * KS_STRIDE + d8) = r.k;
;   const u32x4 vd = __builtin_bit_cast(u32x4, r.v);
;   const bool odd = key & 1;
;   const unsigned s0 = odd ? vd[0] : vd[2], s1 = odd ? vd[1] : vd[3];
;   const unsigned x0 = (unsigned)__builtin_amdgcn_update_dpp(0, (int)s0, 0x128, 0xf, 0xf, false), x1 = (unsigned)__builtin_amdgcn_update_dpp(0, (int)s1, 0x128, 0xf, 0xf, false);
;   const unsigned m0 = odd ? vd[2] : vd[0], m1 = odd ? vd[3] : vd[1];
;   const unsigned lo0 = odd ? x0 : m0, hi0 = odd ? m0 : x0, lo1 = odd ? x1 : m1, hi1 = odd ? m1 : x1;
;   LAS unsigned* vp = (LAS unsigned*)(Vt + (d8 + (odd ? 4 : 0)) * vstride + vcol0 + (key & ~1));
;   const int rs = vstride >> 1;
;   vp[0] = (lo0 & 0xffffu) | (hi0 << 16); vp[rs] = (lo0 >> 16) | (hi0 & 0xffff0000u);
;   vp[2 * rs] = (lo1 & 0xffffu) | (hi1 << 16); vp[3 * rs] = (lo1 >> 16) | (hi1 & 0xffff0000u);
; }
; DI void nsa_attn_phase(int wv, const P& p_, LAS unsigned char* lds) {
;     ...
;     { const unsigned long long selm = (unsigned long long)SELM[2 * (8 * wid + tl)] | ((unsigned long long)SELM[2 * (8 * wid + tl) + 1] << 32);
;       unsigned long long rem = (unsigned long long)UNI[0] | ((unsigned long long)UNI[1] << 32);
;       m = -1e30f; l = 0.f; zero_o(O);
;       const int jw0 = qi > 8 ? qi - 8 : 0;
; #pragma unroll 1
;       while (rem) {
;         const int j = __builtin_ctzll(rem); rem &= rem - 1ull;
;         kv_store(kvr, KsB[buf], VtB[buf], 68, 0, tid);
;         __syncthreads();
;         { const bool more = rem != 0ull; const int jn = more ? __builtin_ctzll(rem) : jw0;
;           const size_t go = (size_t)(b * SEQ + jn * 64) * ld + g * 64; kv_load(kvr, hb + go + (more ? 1536 : 2048), hb + go + (more ? 1792 : 2304), ld, tid); }
;         attn_tile(KsB[buf], VtB[buf], 68, qf, O, m, l, t, tw, 8, r, h, j * 64, 1, 0x7fffffff, ((selm >> j) & 1ull) != 0ull, btl);
.LBB0_773:
	s_add_i32 s0, 0, 0x22840
	v_mov_b32_e32 v0, s0
	s_waitcnt lgkmcnt(0)
	s_barrier
	ds_read_b64 v[0:1], v0
	v_ashrrev_i32_e32 v217, 3, v130
	v_lshlrev_b32_e32 v218, 3, v130
	v_and_b32_e32 v218, 56, v218
	v_mul_lo_u32 v216, v217, s90
	v_lshl_add_u32 v216, v218, 1, v216
	v_lshlrev_b32_e32 v220, 4, v130
	v_and_b32_e32 v220, 0x70, v220
	v_mul_u32_u24_e32 v221, 0x1600, v217
	v_add_u32_e32 v220, v221, v220
	v_mov_b32_e32 v221, 0
	v_and_b32_e32 v219, 8, v130
	v_lshrrev_b32_e32 v222, 1, v219
	v_or_b32_e32 v222, v218, v222
	v_mul_u32_u24_e32 v222, 0x88, v222
	v_lshlrev_b32_e32 v217, 1, v217
	v_and_b32_e32 v217, -4, v217
	v_add_u32_e32 v217, v222, v217
	v_mov_b32_e32 v218, v219
	v_add_u32_e32 v219, v134, v159
	v_ashrrev_i32_e32 v246, 3, v130
	v_lshlrev_b32_e32 v246, 7, v246
	v_and_b32_e32 v247, 7, v130
	v_lshl_add_u32 v246, v247, 4, v246
	v_and_b32_e32 v247, 63, v130
	v_lshrrev_b32_e32 v248, 5, v247
	v_bfe_u32 v249, v247, 2, 2
	v_lshl_add_u32 v248, v248, 2, v249
	v_lshlrev_b32_e32 v248, 7, v248
	v_bfe_u32 v249, v247, 4, 1
	v_lshl_add_u32 v248, v249, 5, v248
	v_and_b32_e32 v249, 3, v247
	v_lshl_add_u32 v247, v249, 3, v248
	ds_read_b32 v224, v158 offset:512
	v_and_b32_e32 v226, 3, v130
	v_mul_u32_u24_e32 v226, 0x210, v226
	v_add_u32_e32 v226, 0x21dfc, v226
	v_mov_b32_e32 v227, 0xf149f2ca
	ds_write_b32 v226, v227
	s_max_i32 s78, s95, 8
	s_add_i32 s71, s78, -8
	s_lshl_b32 s0, s40, 1
	s_add_u32 s50, s82, s0
	s_waitcnt lgkmcnt(0)
	v_readfirstlane_b32 s60, v0
	v_cmp_eq_u64_e32 vcc, 0, v[0:1]
	v_mul_u32_u24_e32 v0, 0x44, v149
	s_mov_b32 s44, 0xf149f2ca
	v_readfirstlane_b32 s61, v1
	s_addc_u32 s57, s83, 0
	v_lshlrev_b32_e32 v164, 1, v0
	s_cbranch_vccnz .LBB0_791
	v_or_b32_e32 v0, s4, v157
	v_lshl_add_u32 v0, v0, 3, 0
	v_add_u32_e32 v0, 0x22640, v0
	ds_read_b64 v[136:137], v0
	v_mov_b32_e32 v46, v32
	v_mov_b32_e32 v47, v32
	v_mov_b32_e32 v33, v32
	v_mov_b32_e32 v34, v32
	v_mov_b32_e32 v35, v32
	v_mov_b32_e32 v36, v32
	v_mov_b32_e32 v37, v32
	v_mov_b32_e32 v38, v32
	v_mov_b32_e32 v39, v32
	v_mov_b32_e32 v40, v32
	v_mov_b32_e32 v41, v32
	v_mov_b32_e32 v42, v32
	v_mov_b32_e32 v43, v32
	v_mov_b32_e32 v44, v32
	v_mov_b32_e32 v45, v32
	v_mov_b64_e32 v[64:65], v[46:47]
	v_lshlrev_b32_e32 v144, 2, v145
	v_mov_b64_e32 v[62:63], v[44:45]
	v_mov_b64_e32 v[60:61], v[42:43]
	v_mov_b64_e32 v[58:59], v[40:41]
	v_mov_b64_e32 v[56:57], v[38:39]
	v_mov_b64_e32 v[54:55], v[36:37]
	v_mov_b64_e32 v[52:53], v[34:35]
	v_mov_b64_e32 v[50:51], v[32:33]
	v_mov_b64_e32 v[48:49], v[46:47]
	s_sub_i32 s79, s87, 63
	v_not_b32_e32 v146, v144
	v_or_b32_e32 v148, 2, v144
	v_or_b32_e32 v149, 3, v144
	v_or_b32_e32 v150, 8, v144
	v_or_b32_e32 v151, 9, v144
	v_or_b32_e32 v152, 10, v144
	v_or_b32_e32 v153, 11, v144
	v_or_b32_e32 v154, 16, v144
	v_or_b32_e32 v155, 17, v144
	v_or_b32_e32 v165, 18, v144
	v_or_b32_e32 v166, 19, v144
	v_or_b32_e32 v167, 24, v144
	v_or_b32_e32 v168, 25, v144
	v_or_b32_e32 v169, 26, v144
	v_or_b32_e32 v170, 27, v144
	s_mov_b32 s70, 0
	v_mov_b32_e32 v171, 0xf149f2ca
	v_mov_b32_e32 v143, 0
	v_mov_b64_e32 v[46:47], v[44:45]
	v_mov_b64_e32 v[44:45], v[42:43]
	v_mov_b64_e32 v[42:43], v[40:41]
	v_mov_b64_e32 v[40:41], v[38:39]
	v_mov_b64_e32 v[38:39], v[36:37]
	v_mov_b64_e32 v[36:37], v[34:35]
	v_mov_b64_e32 v[34:35], v[32:33]
.LBB0_775:
	s_add_u32 s0, s60, -1
	s_addc_u32 s1, s61, -1
	s_ff1_i32_b64 s8, s[60:61]
	s_and_b64 s[60:61], s[0:1], s[60:61]
	s_cmp_eq_u32 s70, 1
	s_cselect_b32 s0, s58, 0
	s_cselect_b32 s84, s59, s81
	v_add_u32_e32 v3, s0, v216
	v_add_u32_e32 v0, s84, v246
	v_add_u32_e32 v225, s0, v219
	s_waitcnt vmcnt(1)
	ds_write_b128 v3, v[126:129]
	s_waitcnt vmcnt(0)
	ds_write_b128 v0, v[122:125]
	s_waitcnt lgkmcnt(0)
	s_barrier
	ds_read_b128 v[0:3], v225
	ds_read_b128 v[4:7], v225 offset:32
	ds_read_b128 v[8:11], v225 offset:64
	ds_read_b128 v[12:15], v225 offset:96
	ds_read_b128 v[16:19], v225 offset:4608
	ds_read_b128 v[20:23], v225 offset:4640
	ds_read_b128 v[24:27], v225 offset:4672
	ds_read_b128 v[28:31], v225 offset:4704
	s_cmp_eq_u64 s[60:61], 0
	s_cselect_b64 s[64:65], -1, 0
	s_ff1_i32_b64 s6, s[60:61]
	s_and_b64 s[0:1], s[64:65], exec
	s_cselect_b32 s0, s71, s6
	s_movk_i32 s1, 0xc00
	s_movk_i32 s6, 0x1200
	s_cselect_b32 s1, 0x1000, s1
	s_cselect_b32 s6, s6, 0xe00
	s_lshl_b32 s0, s0, 6
	s_add_i32 s0, s0, s93
	s_mul_hi_u32 s7, s0, 0x1600
	s_mulk_i32 s0, 0x1600
	s_add_u32 s9, s50, s0
	s_addc_u32 s7, s57, s7
	s_add_u32 s0, s9, s1
	s_addc_u32 s1, s7, 0
	s_add_u32 s6, s9, s6
	s_addc_u32 s7, s7, 0
	v_lshl_add_u64 v[226:227], v[220:221], 0, s[0:1]
	v_lshl_add_u64 v[230:231], v[220:221], 0, s[6:7]
	s_lshl_b32 s10, s8, 6
	global_load_dwordx4 v[126:129], v[226:227], off
	global_load_dwordx4 v[122:125], v[230:231], off
	v_lshrrev_b64 v[244:245], s8, v[136:137]
	s_sub_i32 s8, s79, s10
	s_cmpk_gt_i32 s8, 0x7f
	s_cselect_b64 s[0:1], -1, 0
	s_cmpk_lt_i32 s8, 0x80
	s_cselect_b64 s[8:9], -1, 0
	s_sub_i32 s11, s10, s87
	s_cmp_eq_u32 s11, 0x80000008
	s_cselect_b64 s[12:13], -1, 0
	v_and_b32_e32 v244, 1, v244
	s_or_b64 s[12:13], s[8:9], s[12:13]
	v_cmp_eq_u32_e64 s[6:7], 1, v244
	s_mov_b64 s[8:9], -1
	s_waitcnt lgkmcnt(4)
	v_mfma_f32_32x32x16_bf16 v[82:97], v[0:3], v[106:109], 0
	v_mfma_f32_32x32x16_bf16 v[82:97], v[4:7], v[110:113], v[82:97]
	v_mfma_f32_32x32x16_bf16 v[82:97], v[8:11], v[114:117], v[82:97]
	v_mfma_f32_32x32x16_bf16 v[82:97], v[12:15], v[118:121], v[82:97]
	s_waitcnt lgkmcnt(0)
	v_mfma_f32_32x32x16_bf16 v[66:81], v[16:19], v[106:109], 0
	v_mfma_f32_32x32x16_bf16 v[66:81], v[20:23], v[110:113], v[66:81]
	v_mfma_f32_32x32x16_bf16 v[66:81], v[24:27], v[114:117], v[66:81]
	v_mfma_f32_32x32x16_bf16 v[66:81], v[28:31], v[118:121], v[66:81]
	s_and_b64 vcc, exec, s[12:13]
	s_cbranch_vccz .LBB0_779
	s_and_b64 vcc, exec, s[8:9]
	s_cbranch_vccnz .LBB0_782

; #define LAS __attribute__((address_space(3)))
; DI unsigned pk2(float a, float b) { typedef __bf16 bf2 __attribute__((ext_vector_type(2))); bf2 v; v[0] = (__bf16)a; v[1] = (__bf16)b; return __builtin_bit_cast(unsigned, v); }
; #define MFMA32(a, b, c) __builtin_amdgcn_mfma_f32_32x32x16_bf16((a), (b), (c), 0, 0, 0)
; DI void attn_pv(const LAS bf16_t* Vt, int vstride, const f32x16 (&p)[2], f32x16 (&O)[2], int r, int h) {
; #pragma unroll
;   for (int sub = 0; sub < 2; ++sub)
; #pragma unroll
;     for (int s2 = 0; s2 < 2; ++s2) {
;       u32x4 pp;
; #pragma unroll
;       for (int j = 0; j < 4; ++j) pp[j] = pk2(p[sub][8 * s2 + 2 * j], p[sub][8 * s2 + 2 * j + 1]);
;       const bf16x8 pf = __builtin_bit_cast(bf16x8, pp);
; #pragma unroll
;       for (int dt = 0; dt < 2; ++dt) {
;         const LAS bf16_t* vp = Vt + (dt * 32 + r) * vstride + sub * 32 + 16 * s2 + 4 * h;
;         const s16x4 lo = *(const LAS s16x4*)vp, hi = *(const LAS s16x4*)(vp + 8);
;         const bf16x8 vf = __builtin_shufflevector(lo, hi, 0, 1, 2, 3, 4, 5, 6, 7);
;         O[dt] = MFMA32(vf, pf, O[dt]);
;       }
;     }
; }
.LBB0_788:
	v_add_u32_e32 v33, s84, v247
	ds_read_b64_tr_b16 v[66:67], v33
	ds_read_b64_tr_b16 v[68:69], v33 offset:1024
	ds_read_b64_tr_b16 v[70:71], v33 offset:64
	ds_read_b64_tr_b16 v[72:73], v33 offset:1088
	ds_read_b64_tr_b16 v[74:75], v33 offset:2048
	ds_read_b64_tr_b16 v[76:77], v33 offset:3072
	ds_read_b64_tr_b16 v[78:79], v33 offset:2112
	ds_read_b64_tr_b16 v[80:81], v33 offset:3136
	ds_read_b64_tr_b16 v[82:83], v33 offset:4096
	ds_read_b64_tr_b16 v[84:85], v33 offset:5120
	ds_read_b64_tr_b16 v[86:87], v33 offset:4160
	ds_read_b64_tr_b16 v[88:89], v33 offset:5184
	v_exp_f32_e32 v31, v141
	s_xor_b32 s70, s70, 1
	s_andn2_b64 vcc, exec, s[64:65]
	v_cvt_pk_bf16_f32 v0, v0, v1
	v_cvt_pk_bf16_f32 v1, v2, v3
	v_cvt_pk_bf16_f32 v2, v4, v5
	v_cvt_pk_bf16_f32 v3, v6, v7
	v_cvt_pk_bf16_f32 v4, v8, v9
	v_cvt_pk_bf16_f32 v5, v10, v11
	v_cvt_pk_bf16_f32 v6, v12, v13
	v_cvt_pk_bf16_f32 v7, v14, v15
	s_waitcnt lgkmcnt(8)
	v_mfma_f32_32x32x16_bf16 v[50:65], v[66:69], v[0:3], v[50:65]
	v_mfma_f32_32x32x16_bf16 v[34:49], v[70:73], v[0:3], v[34:49]
	ds_read_b64_tr_b16 v[90:91], v33 offset:6144
	ds_read_b64_tr_b16 v[92:93], v33 offset:7168
	ds_read_b64_tr_b16 v[94:95], v33 offset:6208
	ds_read_b64_tr_b16 v[96:97], v33 offset:7232
	v_cvt_pk_bf16_f32 v8, v16, v17
	v_cvt_pk_bf16_f32 v9, v18, v19
	v_cvt_pk_bf16_f32 v10, v20, v21
	v_cvt_pk_bf16_f32 v11, v22, v23
	s_waitcnt lgkmcnt(8)
	v_mfma_f32_32x32x16_bf16 v[50:65], v[74:77], v[4:7], v[50:65]
	v_mfma_f32_32x32x16_bf16 v[34:49], v[78:81], v[4:7], v[34:49]
	v_cvt_pk_bf16_f32 v12, v24, v25
	v_cvt_pk_bf16_f32 v13, v26, v27
	v_cvt_pk_bf16_f32 v14, v28, v29
	v_cvt_pk_bf16_f32 v15, v30, v31
	v_add_f32_e32 v33, v31, v140
	v_add_f32_e32 v143, v33, v143
	s_waitcnt lgkmcnt(4)
	v_mfma_f32_32x32x16_bf16 v[50:65], v[82:85], v[8:11], v[50:65]
	v_mfma_f32_32x32x16_bf16 v[34:49], v[86:89], v[8:11], v[34:49]
	s_waitcnt lgkmcnt(0)
	v_mfma_f32_32x32x16_bf16 v[50:65], v[90:93], v[12:15], v[50:65]
	v_mfma_f32_32x32x16_bf16 v[34:49], v[94:97], v[12:15], v[34:49]
	s_cbranch_vccz .LBB0_790
	v_mov_b32_e32 v171, v139
	s_branch .LBB0_775

; #define LAS __attribute__((address_space(3)))
; DI void kv_store(const KVRegs& r, LAS bf16_t* Ks, LAS bf16_t* Vt, int vstride, int vcol0, int tid) {
;   asm volatile("" : "+v"(tid));
;   const int key = tid >> 3, d8 = (tid & 7) * 8;
;   *(LAS u32x4*)(Ks + key * KS_STRIDE + d8) = r.k;
;   const u32x4 vd = __builtin_bit_cast(u32x4, r.v);
;   const bool odd = key & 1;
;   const unsigned s0 = odd ? vd[0] : vd[2], s1 = odd ? vd[1] : vd[3];
;   const unsigned x0 = (unsigned)__builtin_amdgcn_update_dpp(0, (int)s0, 0x128, 0xf, 0xf, false), x1 = (unsigned)__builtin_amdgcn_update_dpp(0, (int)s1, 0x128, 0xf, 0xf, false);
;   const unsigned m0 = odd ? vd[2] : vd[0], m1 = odd ? vd[3] : vd[1];
;   const unsigned lo0 = odd ? x0 : m0, hi0 = odd ? m0 : x0, lo1 = odd ? x1 : m1, hi1 = odd ? m1 : x1;
;   LAS unsigned* vp = (LAS unsigned*)(Vt + (d8 + (odd ? 4 : 0)) * vstride + vcol0 + (key & ~1));
;   const int rs = vstride >> 1;
;   vp[0] = (lo0 & 0xffffu) | (hi0 << 16); vp[rs] = (lo0 >> 16) | (hi0 & 0xffff0000u);
;   vp[2 * rs] = (lo1 & 0xffffu) | (hi1 << 16); vp[3 * rs] = (lo1 >> 16) | (hi1 & 0xffff0000u);
; }
; DI void nsa_attn_phase(int wv, const P& p_, LAS unsigned char* lds) {
;     ...
;       for (int j = (qi > 8 ? qi - 8 : 0); j <= qi; ++j) {
;         kv_store(kvr, KsB[buf], VtB[buf], 68, 0, tid);
;         __syncthreads();
;         if (j < qi) { const size_t go = (size_t)(b * SEQ + (j + 1) * 64) * ld + g * 64; kv_load(kvr, hb + go + 2048, hb + go + 2304, ld, tid); }
.LBB0_794:
	s_add_i32 s17, s17, 1
	s_cmp_eq_u32 s70, 1
	s_cselect_b32 s0, s58, 0
	s_cselect_b32 s18, s59, s81
	v_add_u32_e32 v36, s0, v216
	v_add_u32_e32 v33, s18, v246
	s_cmp_ge_i32 s17, s95
	s_cselect_b64 s[10:11], -1, 0
	s_waitcnt vmcnt(1)
	ds_write_b128 v36, v[126:129]
	s_waitcnt vmcnt(0)
	ds_write_b128 v33, v[122:125]
	s_and_b64 vcc, exec, s[10:11]
	s_waitcnt lgkmcnt(0)
	s_barrier
	s_cbranch_vccnz .LBB0_796
	s_mul_i32 s6, s16, 0x1600
	s_mul_hi_i32 s1, s16, 0x1600
	s_add_u32 s6, s50, s6
	s_addc_u32 s7, s57, s1
	s_add_u32 s6, s6, 0x1000
	s_addc_u32 s7, s7, 0
	v_lshl_add_u64 v[34:35], v[220:221], 0, s[6:7]
	global_load_dwordx4 v[126:129], v[34:35], off
	global_load_dwordx4 v[122:125], v[34:35], off offset:512

; #define LAS __attribute__((address_space(3)))
; DI unsigned pk2(float a, float b) { typedef __bf16 bf2 __attribute__((ext_vector_type(2))); bf2 v; v[0] = (__bf16)a; v[1] = (__bf16)b; return __builtin_bit_cast(unsigned, v); }
; #define MFMA32(a, b, c) __builtin_amdgcn_mfma_f32_32x32x16_bf16((a), (b), (c), 0, 0, 0)
; DI void attn_pv(const LAS bf16_t* Vt, int vstride, const f32x16 (&p)[2], f32x16 (&O)[2], int r, int h) {
; #pragma unroll
;   for (int sub = 0; sub < 2; ++sub)
; #pragma unroll
;     for (int s2 = 0; s2 < 2; ++s2) {
;       u32x4 pp;
; #pragma unroll
;       for (int j = 0; j < 4; ++j) pp[j] = pk2(p[sub][8 * s2 + 2 * j], p[sub][8 * s2 + 2 * j + 1]);
;       const bf16x8 pf = __builtin_bit_cast(bf16x8, pp);
; #pragma unroll
;       for (int dt = 0; dt < 2; ++dt) {
;         const LAS bf16_t* vp = Vt + (dt * 32 + r) * vstride + sub * 32 + 16 * s2 + 4 * h;
;         const s16x4 lo = *(const LAS s16x4*)vp, hi = *(const LAS s16x4*)(vp + 8);
;         const bf16x8 vf = __builtin_shufflevector(lo, hi, 0, 1, 2, 3, 4, 5, 6, 7);
;         O[dt] = MFMA32(vf, pf, O[dt]);
;       }
;     }
; }
; DI void nsa_attn_phase(int wv, const P& p_, LAS unsigned char* lds) {
;     ...
;         attn_tile(KsB[buf], VtB[buf], 68, qf, O, m, l, t, tw, 8, r, h, j * 64, 1, 512, true, btl);
;         buf ^= 1;
;       }
.LBB0_807:
	v_exp_f32_e32 v33, v155
	v_add_u32_e32 v214, s18, v247
	ds_read_b64_tr_b16 v[38:39], v214
	ds_read_b64_tr_b16 v[40:41], v214 offset:1024
	ds_read_b64_tr_b16 v[42:43], v214 offset:64
	ds_read_b64_tr_b16 v[44:45], v214 offset:1088
	ds_read_b64_tr_b16 v[46:47], v214 offset:2048
	ds_read_b64_tr_b16 v[48:49], v214 offset:3072
	ds_read_b64_tr_b16 v[50:51], v214 offset:2112
	ds_read_b64_tr_b16 v[52:53], v214 offset:3136
	ds_read_b64_tr_b16 v[54:55], v214 offset:4096
	ds_read_b64_tr_b16 v[56:57], v214 offset:5120
	ds_read_b64_tr_b16 v[58:59], v214 offset:4160
	ds_read_b64_tr_b16 v[60:61], v214 offset:5184
	ds_read_b64_tr_b16 v[62:63], v214 offset:6144
	ds_read_b64_tr_b16 v[64:65], v214 offset:7168
	s_xor_b32 s70, s70, 1
	s_add_i32 s14, s14, 64
	s_sub_i32 s15, s15, 64
	s_add_i32 s16, s16, 64
	v_cvt_pk_bf16_f32 v34, v205, v206
	v_cvt_pk_bf16_f32 v35, v207, v209
	v_cvt_pk_bf16_f32 v36, v210, v211
	v_cvt_pk_bf16_f32 v37, v212, v213
	v_add_f32_e32 v215, v33, v154
	v_add_f32_e32 v167, v215, v167
	s_waitcnt lgkmcnt(10)
	v_mfma_f32_32x32x16_bf16 v[16:31], v[38:41], v[34:37], v[16:31]
	v_mfma_f32_32x32x16_bf16 v[0:15], v[42:45], v[34:37], v[0:15]
	ds_read_b64_tr_b16 v[38:39], v214 offset:6208
	ds_read_b64_tr_b16 v[40:41], v214 offset:7232
	v_cvt_pk_bf16_f32 v34, v171, v172
	v_cvt_pk_bf16_f32 v35, v173, v174
	v_cvt_pk_bf16_f32 v36, v176, v178
	v_cvt_pk_bf16_f32 v37, v181, v185
	s_waitcnt lgkmcnt(8)
	s_nop 0
	v_mfma_f32_32x32x16_bf16 v[16:31], v[46:49], v[34:37], v[16:31]
	v_mfma_f32_32x32x16_bf16 v[0:15], v[50:53], v[34:37], v[0:15]
	v_cvt_pk_bf16_f32 v34, v179, v182
	v_cvt_pk_bf16_f32 v35, v184, v186
	v_cvt_pk_bf16_f32 v36, v189, v190
	v_cvt_pk_bf16_f32 v37, v191, v192
	s_waitcnt lgkmcnt(4)
	s_nop 0
	v_mfma_f32_32x32x16_bf16 v[16:31], v[54:57], v[34:37], v[16:31]
	v_mfma_f32_32x32x16_bf16 v[0:15], v[58:61], v[34:37], v[0:15]
	v_cvt_pk_bf16_f32 v34, v175, v177
	v_cvt_pk_bf16_f32 v35, v180, v183
	v_cvt_pk_bf16_f32 v36, v187, v188
	v_cvt_pk_bf16_f32 v37, v152, v33
	s_waitcnt lgkmcnt(0)
	s_nop 0
	v_mfma_f32_32x32x16_bf16 v[16:31], v[62:65], v[34:37], v[16:31]
	v_mfma_f32_32x32x16_bf16 v[0:15], v[38:41], v[34:37], v[0:15]
	s_and_b64 vcc, exec, s[10:11]
	s_cbranch_vccnz .LBB0_809
	v_mov_b32_e32 v170, v151
	s_branch .LBB0_794
